# P4 MLA up-projection GEMM skips the structurally-zero K ranges of its packed weight (per column tile K window), column tiles rotated per row group for balance
# speedup vs baseline: 1.0387x; 1.0045x over previous
.LBB0_234:
	s_or_b64 exec, exec, s[0:1]
	v_readlane_b32 s8, v252, 18
	v_readlane_b32 s12, v252, 22
	v_readlane_b32 s13, v252, 23
	s_add_u32 s74, s12, 0x15c91600
	s_addc_u32 s75, s13, 0
	s_add_u32 s24, s12, 0x3200000
	s_addc_u32 s25, s13, 0
	s_lshl_b32 s5, s54, 5
	v_readlane_b32 s14, v252, 24
	v_readlane_b32 s15, v252, 25
	s_add_u32 s88, s12, 0x3c91600
	s_mul_i32 s0, s15, s14
	s_addc_u32 s89, s13, 0
	s_lshl_b32 s29, s14, 5
	s_mul_i32 s70, s0, s33
	s_add_u32 s0, s12, 0x338e200
	v_readlane_b32 s10, v252, 20
	s_addc_u32 s1, s13, 0
	v_readlane_b32 s11, v252, 21
	s_add_u32 s10, s12, 0x338e400
	s_addc_u32 s11, s13, 0
	s_add_u32 s26, s12, 0x338e500
	s_addc_u32 s27, s13, 0
	s_add_u32 s30, s12, 0x338e600
	s_addc_u32 s31, s13, 0
	s_add_u32 s90, s12, 0x338e700
	s_addc_u32 s91, s13, 0
	s_add_u32 s22, s12, 0x338e800
	s_addc_u32 s23, s13, 0
	s_add_u32 s78, s12, 0x338e900
	v_writelane_b32 v253, s0, 28
	s_addc_u32 s79, s13, 0
	v_readlane_b32 s9, v252, 19
	v_writelane_b32 v253, s1, 29
	s_add_u32 s0, s12, 0x338ea00
	s_addc_u32 s1, s13, 0
	v_writelane_b32 v253, s0, 30
	v_exp_f32_e32 v210, 0xbfd49a78
	v_writelane_b32 v255, s26, 0
	v_writelane_b32 v253, s1, 31
	s_add_u32 s0, s12, 0x338eb00
	s_addc_u32 s1, s13, 0
	v_writelane_b32 v253, s0, 32
	v_writelane_b32 v255, s27, 1
	v_writelane_b32 v255, s30, 2
	v_writelane_b32 v253, s1, 33
	s_add_u32 s0, s12, 0x338ec00
	s_addc_u32 s1, s13, 0
	v_writelane_b32 v253, s0, 34
	v_exp_f32_e32 v235, 0xc0549a78
	s_waitcnt lgkmcnt(0)
	v_mbcnt_lo_u32_b32 v0, -1, 0
	v_writelane_b32 v253, s1, 35
	s_add_u32 s0, s12, 0x338ed00
	s_addc_u32 s1, s13, 0
	v_writelane_b32 v253, s0, 36
	v_writelane_b32 v255, s31, 3
	v_mbcnt_hi_u32_b32 v224, -1, v0
	v_writelane_b32 v253, s1, 37
	s_add_u32 s0, s12, 0x338ee00
	s_addc_u32 s1, s13, 0
	v_writelane_b32 v253, s0, 38
	v_writelane_b32 v255, s29, 4
	v_and_b32_e32 v0, 64, v224
	v_writelane_b32 v253, s1, 39
	s_add_u32 s0, s12, 0x338ef00
	s_addc_u32 s1, s13, 0
	v_writelane_b32 v253, s0, 40
	v_writelane_b32 v255, s88, 5
	v_mov_b32_e32 v1, 0
	v_writelane_b32 v253, s1, 41
	s_add_u32 s0, s12, 0x338f000
	s_addc_u32 s1, s13, 0
	v_writelane_b32 v253, s0, 42
	v_mov_b32_e32 v220, 0x358637bd
	v_mov_b32_e32 v221, 0x1000
	v_writelane_b32 v253, s1, 43
	s_add_u32 s0, s12, 0x338f100
	s_addc_u32 s1, s13, 0
	v_writelane_b32 v253, s0, 44
	v_mov_b32_e32 v229, 0x3ecc95a3
	v_add_u32_e32 v225, 64, v0
	v_writelane_b32 v253, s1, 45
	s_add_u32 s0, s12, 0x338f200
	s_addc_u32 s1, s13, 0
	v_writelane_b32 v253, s0, 46
	v_xor_b32_e32 v228, 32, v224
	v_xor_b32_e32 v227, 16, v224
	v_writelane_b32 v253, s1, 47
	s_add_u32 s0, s12, 0x338f300
	s_addc_u32 s1, s13, 0
	v_writelane_b32 v253, s0, 48
	v_xor_b32_e32 v226, 8, v224
	v_mov_b32_e32 v234, 0x7f800000
	v_writelane_b32 v253, s1, 49
	s_add_u32 s0, s12, 0x3391400
	s_addc_u32 s1, s13, 0
	v_writelane_b32 v253, s0, 50
	s_mov_b32 s71, 0x38e38e39
	s_movk_i32 s73, 0xf700
	v_writelane_b32 v253, s1, 51
	s_add_u32 s0, s12, 0x3391500
	s_addc_u32 s1, s13, 0
	s_add_u32 s80, s12, 0x1ec91600
	v_writelane_b32 v253, s0, 52
	s_addc_u32 s81, s13, 0
	s_mov_b32 s93, 0x800000
	v_writelane_b32 v253, s1, 53
	s_add_u32 s0, s12, 0x36b11600
	s_addc_u32 s1, s13, 0
	v_writelane_b32 v253, s0, 54
	s_movk_i32 s28, 0x2000
	s_mov_b32 s61, 0x11fff
	v_writelane_b32 v253, s1, 55
	s_add_u32 s0, s12, 0x3e711600
	s_addc_u32 s1, s13, 0
	v_writelane_b32 v253, s0, 56
	s_mov_b32 s97, 0x42800000
	s_movk_i32 s95, 0xf40
	v_writelane_b32 v253, s1, 57
	s_add_u32 s0, s12, 0x3e831600
	s_addc_u32 s1, s13, 0
	v_writelane_b32 v253, s0, 58
	s_ashr_i32 s59, s54, 31
	s_ashr_i32 s55, s14, 31
	v_writelane_b32 v253, s1, 59
	s_lshr_b32 s0, s59, 29
	s_add_i32 s0, s54, s0
	s_ashr_i32 s1, s0, 3
	s_and_b32 s0, s0, -8
	s_sub_i32 s6, s54, s0
	s_add_u32 s0, s12, 0x3000000
	v_writelane_b32 v253, s0, 60
	s_addc_u32 s0, s13, 0
	s_cmpk_lt_i32 s54, 0x480
	v_writelane_b32 v253, s0, 61
	s_cselect_b64 s[8:9], -1, 0
	v_writelane_b32 v253, s8, 62
	s_movk_i32 s33, 0x7fff
	s_movk_i32 s60, 0x210
	v_writelane_b32 v253, s9, 63
	s_add_u32 s8, s12, 0x38f11600
	s_addc_u32 s9, s13, 0
	v_writelane_b32 v254, s8, 0
	s_mov_b32 s53, 0x1ed49000
	s_mov_b32 s72, 0x429cc470
	v_writelane_b32 v254, s9, 1
	s_add_u32 s8, s12, 0x2ff11600
	s_addc_u32 s9, s13, 0
	v_writelane_b32 v254, s8, 2
	s_add_u32 s0, s12, 0x338c000
	s_mov_b64 s[62:63], -1
	v_writelane_b32 v254, s9, 3
	v_writelane_b32 v254, s0, 4
	s_addc_u32 s0, s13, 0
	v_writelane_b32 v254, s0, 5
	s_add_u32 s0, s12, 0x3b91600
	v_writelane_b32 v254, s0, 6
	s_addc_u32 s0, s13, 0
	v_writelane_b32 v254, s0, 7
	s_add_u32 s0, s12, 0x3391600
	v_writelane_b32 v254, s0, 8
	s_addc_u32 s0, s13, 0
	v_writelane_b32 v254, s0, 9
	s_add_u32 s0, s12, 0x3d711600
	v_writelane_b32 v254, s0, 10
	s_addc_u32 s0, s13, 0
	s_add_u32 s8, s12, 0x3b311600
	v_writelane_b32 v254, s0, 11
	s_addc_u32 s9, s13, 0
	v_writelane_b32 v254, s8, 12
	s_mov_b64 s[56:57], 0x80
	s_mov_b32 s58, 0x3b800000
	v_writelane_b32 v254, s9, 13
	s_add_u32 s8, s12, 0x32311600
	s_addc_u32 s9, s13, 0
	v_writelane_b32 v254, s8, 14
	s_add_u32 s0, s12, 0xb00000
	s_mov_b32 s92, 0x358637bd
	v_writelane_b32 v254, s9, 15
	v_writelane_b32 v254, s0, 16
	s_addc_u32 s0, s13, 0
	v_writelane_b32 v254, s0, 17
	s_add_u32 s0, s12, 0xf00000
	v_writelane_b32 v254, s0, 18
	s_addc_u32 s0, s13, 0
	v_writelane_b32 v254, s0, 19
	s_add_u32 s0, s12, 0x2500000
	v_writelane_b32 v254, s0, 20
	s_addc_u32 s0, s13, 0
	v_writelane_b32 v254, s0, 21
	s_cmp_lt_i32 s6, 0
	s_movk_i32 s0, 0x91
	s_cselect_b32 s0, s0, 0x90
	s_mul_i32 s0, s6, s0
	s_add_i32 s0, s0, s1
	v_writelane_b32 v254, s1, 22
	s_ashr_i32 s1, s0, 31
	s_lshr_b32 s1, s1, 27
	s_add_i32 s1, s0, s1
	s_and_b32 s3, s1, 0xffe0
	s_sub_i32 s0, s0, s3
	s_bfe_i32 s3, s0, 0x80000
	s_bfe_u32 s3, s3, 0x3000c
	s_add_i32 s3, s0, s3
	s_and_b32 s4, s3, 0xf8
	s_sub_i32 s0, s0, s4
	s_ashr_i32 s1, s1, 5
	s_lshl_b32 s1, s1, 3
	s_sext_i32_i8 s0, s0
	s_add_i32 s4, s1, s0
	s_bfe_i32 s0, s3, 0x80000
	s_sext_i32_i16 s0, s0
	s_ashr_i32 s1, s0, 3
	s_lshr_b32 s0, s0, 3
	s_lshr_b32 s3, s4, 3
	s_add_i32 s1, s1, s3
	s_and_b32 s1, s1, 3
	s_mov_b32 s0, s1
	v_writelane_b32 v254, s1, 23
	s_bfe_i64 s[0:1], s[0:1], 0x100000
	s_lshl_b64 s[0:1], s[0:1], 18
	s_lshr_b32 s3, s0, 19
	s_lshl_b32 s3, s3, 9
	s_add_u32 s0, s0, s3
	v_writelane_b32 v254, s0, 24
	s_mov_b32 s9, 0
	v_writelane_b32 v252, s8, 0
	v_writelane_b32 v254, s1, 25
	v_writelane_b32 v254, s6, 26
	s_lshr_b32 s0, s6, 31
	s_mul_i32 s1, s4, 0xf4000
	v_writelane_b32 v254, s0, 27
	s_mul_hi_i32 s0, s4, 0xf4000
	s_add_u32 s6, s80, s1
	v_writelane_b32 v254, s4, 28
	s_addc_u32 s7, s81, s0
	s_add_u32 s6, s6, s3
	s_addc_u32 s7, s7, 0
	s_add_u32 s0, s6, 0x7a000
	v_writelane_b32 v254, s6, 29
	s_addc_u32 s1, s7, 0
	v_writelane_b32 v252, s9, 1
	v_writelane_b32 v254, s7, 30
	v_writelane_b32 v254, s0, 31
	v_writelane_b32 v252, s10, 2
	v_writelane_b32 v252, s11, 3
	v_writelane_b32 v254, s1, 32
	v_writelane_b32 v254, s5, 33
	s_or_b32 s0, s5, 3
	v_writelane_b32 v254, s0, 34
	s_add_i32 s0, 0, 0x20000
	v_writelane_b32 v254, s0, 35
	s_add_i32 s0, 0, 0x20004
	v_writelane_b32 v254, s0, 36
	s_add_i32 s0, 0, 0xa100
	v_writelane_b32 v252, s12, 4
	v_writelane_b32 v254, s0, 37
	s_add_i32 s0, 0, 0x3c0
	v_writelane_b32 v252, s13, 5
	v_writelane_b32 v254, s0, 38
	s_add_i32 s0, 0, 0x5c0
	v_writelane_b32 v252, s14, 6
	v_writelane_b32 v254, s0, 39
	s_add_i32 s0, 0, 0x7c0
	v_writelane_b32 v252, s15, 7
	v_writelane_b32 v254, s0, 40
	s_add_i32 s0, 0, 0x9c0
	v_writelane_b32 v252, s16, 8
	v_writelane_b32 v254, s0, 41
	s_add_i32 s0, 0, 0xbc0
	v_writelane_b32 v252, s17, 9
	v_writelane_b32 v254, s0, 42
	s_add_i32 s0, 0, 0xdc0
	v_writelane_b32 v252, s18, 10
	v_writelane_b32 v254, s0, 43
	s_add_i32 s0, 0, 0xfc0
	v_writelane_b32 v252, s19, 11
	v_writelane_b32 v254, s0, 44
	s_add_i32 s0, 0, 0x11c0
	v_writelane_b32 v252, s20, 12
	v_writelane_b32 v254, s0, 45
	v_writelane_b32 v252, s21, 13
	v_writelane_b32 v252, s22, 14
	v_writelane_b32 v254, s70, 46
	v_writelane_b32 v252, s23, 15
	v_writelane_b32 v254, s10, 47
	s_mov_b32 s0, s54
	s_mov_b64 s[4:5], 0
	v_writelane_b32 v254, s11, 48
	v_writelane_b32 v254, s90, 49
	s_mov_b64 s[2:3], 0x40000
	s_mov_b32 s94, 0x3e38aa3b
	v_writelane_b32 v254, s91, 50
	v_writelane_b32 v254, s22, 51
	s_mov_b32 s96, 0x3e16c740
	s_mov_b32 s52, 0
	v_writelane_b32 v254, s23, 52
	v_writelane_b32 v254, s78, 53
	v_writelane_b32 v255, s89, 6
	s_nop 0
	v_writelane_b32 v254, s79, 54
	v_writelane_b32 v254, s80, 55
	s_barrier
	s_nop 0
	v_writelane_b32 v254, s81, 56
	v_writelane_b32 v254, s0, 57
	s_nop 1
	v_writelane_b32 v254, s1, 58
	v_writelane_b32 v254, s74, 59
	s_nop 1
	v_writelane_b32 v254, s75, 60
	v_writelane_b32 v254, s55, 61
	v_writelane_b32 v254, s24, 62
	s_nop 1
	v_writelane_b32 v254, s25, 63
	s_branch .LBB0_237

.LBB0_517:
	v_readlane_b32 s36, v252, 18
	s_add_i32 s61, s61, 1
	v_readlane_b32 s42, v252, 24
	s_mul_i32 s0, s61, s55
	s_mul_hi_u32 s1, s61, s42
	s_add_i32 s1, s1, s0
	s_mul_i32 s0, s61, s42
	s_add_u32 s14, s0, s54
	s_addc_u32 s15, s1, s59
	v_mov_b64_e32 v[2:3], 0x480
	v_cmp_lt_i64_e64 s[8:9], s[14:15], v[2:3]
	v_mov_b64_e32 v[2:3], 0x47f
	v_cmp_gt_i64_e64 s[0:1], s[14:15], v[2:3]
	s_and_b64 vcc, exec, s[0:1]
	v_readlane_b32 s37, v252, 19
	v_readlane_b32 s38, v252, 20
	v_readlane_b32 s39, v252, 21
	v_readlane_b32 s40, v252, 22
	v_readlane_b32 s41, v252, 23
	v_readlane_b32 s43, v252, 25
	s_cbranch_vccnz .LBB0_519
	s_ashr_i32 s6, s14, 31
	s_lshr_b32 s6, s6, 29
	s_add_i32 s6, s14, s6
	s_ashr_i32 s7, s6, 3
	s_and_b32 s6, s6, -8
	s_sub_i32 s6, s14, s6
	s_cmp_lt_i32 s6, 0
	s_movk_i32 s14, 0x91
	s_cselect_b32 s14, s14, 0x90
	s_mul_i32 s6, s6, s14
	s_add_i32 s6, s6, s7
	s_ashr_i32 s7, s6, 31
	s_lshr_b32 s7, s7, 27
	s_add_i32 s7, s6, s7
	s_ashr_i32 s14, s7, 5
	s_lshl_b32 s14, s14, 3
	s_sub_i32 s15, 0x120, s14
	s_min_i32 s15, s15, 8
	s_abs_i32 s16, s15
	v_cvt_f32_u32_e32 v2, s16
	s_sub_i32 s18, 0, s16
	s_andn2_b32 s7, s7, 31
	s_sub_i32 s7, s6, s7
	v_rcp_iflag_f32_e32 v2, v2
	s_abs_i32 s6, s7
	s_xor_b32 s17, s7, s15
	s_ashr_i32 s17, s17, 31
	v_mul_f32_e32 v2, 0x4f7ffffe, v2
	v_cvt_u32_f32_e32 v2, v2
	s_nop 0
	v_readfirstlane_b32 s19, v2
	s_mul_i32 s18, s18, s19
	s_mul_hi_u32 s18, s19, s18
	s_add_i32 s19, s19, s18
	s_mul_hi_u32 s18, s6, s19
	s_mul_i32 s19, s18, s16
	s_sub_i32 s6, s6, s19
	s_add_i32 s62, s18, 1
	s_sub_i32 s19, s6, s16
	s_cmp_ge_u32 s6, s16
	s_cselect_b32 s18, s62, s18
	s_cselect_b32 s6, s19, s6
	s_add_i32 s19, s18, 1
	s_cmp_ge_u32 s6, s16
	s_cselect_b32 s6, s19, s18
	s_xor_b32 s6, s6, s17
	s_sub_i32 s6, s6, s17
	s_mul_i32 s15, s6, s15
	s_sub_i32 s7, s7, s15
	s_add_i32 s62, s14, s7
	s_lshr_b32 s18, s62, 3
	s_add_i32 s6, s6, s18
	s_and_b32 s6, s6, 3
.LBB0_519:
	s_andn2_b64 vcc, exec, s[8:9]
	s_mov_b64 s[14:15], s[10:11]
	s_cbranch_vccnz .LBB0_521
	s_mul_i32 s14, s62, 0xf4000
	s_mul_hi_i32 s7, s62, 0xf4000
	s_add_u32 s14, s80, s14
	s_addc_u32 s15, s81, s7
	s_lshr_b32 s18, s6, 1
	s_lshl_b32 s18, s18, 9
	s_add_u32 s14, s14, s18
	s_addc_u32 s15, s15, 0
.LBB0_521:
	s_ashr_i32 s7, s6, 31
	s_lshl_b64 s[16:17], s[6:7], 18
	s_add_u32 s16, s5, s16
	s_addc_u32 s17, s22, s17
	s_lshr_b32 s18, s6, 1
	s_lshl_b32 s18, s18, 9
	s_add_u32 s16, s16, s18
	s_addc_u32 s17, s17, 0
	s_and_b64 s[8:9], s[8:9], exec
	s_cselect_b32 s7, s17, s13
	s_cselect_b32 s63, s16, s12
	s_add_u32 s64, s12, 0x100
	v_mov_b32_e32 v2, 0
	s_addc_u32 s65, s13, 0
	s_cmp_eq_u32 s21, 1
	s_cselect_b32 s72, -2, 2
	s_cmp_eq_u32 s21, 3
	s_cselect_b32 s72, 4, s72
	v_mov_b32_e32 v3, v2
	v_mov_b32_e32 v4, v2
	v_mov_b32_e32 v5, v2
	v_mov_b32_e32 v6, v2
	v_mov_b32_e32 v7, v2
	v_mov_b32_e32 v8, v2
	v_mov_b32_e32 v9, v2
	v_mov_b32_e32 v18, v2
	v_mov_b32_e32 v19, v2
	v_mov_b32_e32 v20, v2
	v_mov_b32_e32 v21, v2
	v_mov_b32_e32 v22, v2
	v_mov_b32_e32 v23, v2
	v_mov_b32_e32 v24, v2
	v_mov_b32_e32 v25, v2
	v_mov_b32_e32 v34, v2
	v_mov_b32_e32 v35, v2
	v_mov_b32_e32 v36, v2
	v_mov_b32_e32 v37, v2
	v_mov_b32_e32 v38, v2
	v_mov_b32_e32 v39, v2
	v_mov_b32_e32 v40, v2
	v_mov_b32_e32 v41, v2
	v_mov_b32_e32 v50, v2
	v_mov_b32_e32 v51, v2
	v_mov_b32_e32 v52, v2
	v_mov_b32_e32 v53, v2
	v_mov_b32_e32 v54, v2
	v_mov_b32_e32 v55, v2
	v_mov_b32_e32 v56, v2
	v_mov_b32_e32 v57, v2
	v_mov_b32_e32 v10, v2
	v_mov_b32_e32 v11, v2
	v_mov_b32_e32 v12, v2
	v_mov_b32_e32 v13, v2
	v_mov_b32_e32 v14, v2
	v_mov_b32_e32 v15, v2
	v_mov_b32_e32 v16, v2
	v_mov_b32_e32 v17, v2
	v_mov_b32_e32 v26, v2
	v_mov_b32_e32 v27, v2
	v_mov_b32_e32 v28, v2
	v_mov_b32_e32 v29, v2
	v_mov_b32_e32 v30, v2
	v_mov_b32_e32 v31, v2
	v_mov_b32_e32 v32, v2
	v_mov_b32_e32 v33, v2
	v_mov_b32_e32 v42, v2
	v_mov_b32_e32 v43, v2
	v_mov_b32_e32 v44, v2
	v_mov_b32_e32 v45, v2
	v_mov_b32_e32 v46, v2
	v_mov_b32_e32 v47, v2
	v_mov_b32_e32 v48, v2
	v_mov_b32_e32 v49, v2
	v_mov_b32_e32 v58, v2
	v_mov_b32_e32 v59, v2
	v_mov_b32_e32 v60, v2
	v_mov_b32_e32 v61, v2
	v_mov_b32_e32 v62, v2
	v_mov_b32_e32 v63, v2
	v_mov_b32_e32 v64, v2
	v_mov_b32_e32 v65, v2
	v_mov_b32_e32 v66, v2
	v_mov_b32_e32 v67, v2
	v_mov_b32_e32 v68, v2
	v_mov_b32_e32 v69, v2
	v_mov_b32_e32 v70, v2
	v_mov_b32_e32 v71, v2
	v_mov_b32_e32 v72, v2
	v_mov_b32_e32 v73, v2
	v_mov_b32_e32 v82, v2
	v_mov_b32_e32 v83, v2
	v_mov_b32_e32 v84, v2
	v_mov_b32_e32 v85, v2
	v_mov_b32_e32 v86, v2
	v_mov_b32_e32 v87, v2
	v_mov_b32_e32 v88, v2
	v_mov_b32_e32 v89, v2
	v_mov_b32_e32 v98, v2
	v_mov_b32_e32 v99, v2
	v_mov_b32_e32 v100, v2
	v_mov_b32_e32 v101, v2
	v_mov_b32_e32 v102, v2
	v_mov_b32_e32 v103, v2
	v_mov_b32_e32 v104, v2
	v_mov_b32_e32 v105, v2
	v_mov_b32_e32 v122, v2
	v_mov_b32_e32 v123, v2
	v_mov_b32_e32 v124, v2
	v_mov_b32_e32 v125, v2
	v_mov_b32_e32 v126, v2
	v_mov_b32_e32 v127, v2
	v_mov_b32_e32 v128, v2
	v_mov_b32_e32 v129, v2
	v_mov_b32_e32 v74, v2
	v_mov_b32_e32 v75, v2
	v_mov_b32_e32 v76, v2
	v_mov_b32_e32 v77, v2
	v_mov_b32_e32 v78, v2
	v_mov_b32_e32 v79, v2
	v_mov_b32_e32 v80, v2
	v_mov_b32_e32 v81, v2
	v_mov_b32_e32 v90, v2
	v_mov_b32_e32 v91, v2
	v_mov_b32_e32 v92, v2
	v_mov_b32_e32 v93, v2
	v_mov_b32_e32 v94, v2
	v_mov_b32_e32 v95, v2
	v_mov_b32_e32 v96, v2
	v_mov_b32_e32 v97, v2
	v_mov_b32_e32 v106, v2
	v_mov_b32_e32 v107, v2
	v_mov_b32_e32 v108, v2
	v_mov_b32_e32 v109, v2
	v_mov_b32_e32 v110, v2
	v_mov_b32_e32 v111, v2
	v_mov_b32_e32 v112, v2
	v_mov_b32_e32 v113, v2
	v_mov_b32_e32 v130, v2
	v_mov_b32_e32 v131, v2
	v_mov_b32_e32 v132, v2
	v_mov_b32_e32 v133, v2
	v_mov_b32_e32 v134, v2
	v_mov_b32_e32 v135, v2
	v_mov_b32_e32 v136, v2
	v_mov_b32_e32 v137, v2
